# v70 + merge K-loop LDS-DMA issue balanced 4/4/4/4 like the other loops (A(k1,half0) stage behind the loop, trip-counter temp moved to s101)
# speedup vs baseline: 1.0150x; 1.0077x over previous
.LBB0_1029:
.LBB0_1030:
	v_add_u32_e32 v0, 0x10000, v230
	ds_read_b128 v[130:133], v0
	ds_read_b128 v[134:137], v0 offset:1024
	ds_read_b128 v[138:141], v0 offset:2048
	ds_read_b128 v[142:145], v0 offset:3072
	v_add_u32_e32 v0, 0x14000, v230
	ds_read_b128 v[146:149], v0
	ds_read_b128 v[150:153], v0 offset:1024
	ds_read_b128 v[154:157], v0 offset:2048
	ds_read_b128 v[158:161], v0 offset:3072
	s_lshl_b32 s55, s20, 7
	s_add_i32 s18, s73, s55
	s_and_b64 s[12:13], s[16:17], exec
	s_cselect_b32 s13, s31, s9
	s_cselect_b32 s12, s30, s8
	s_cselect_b32 s15, s35, s11
	s_cselect_b32 s14, s34, s10
	s_cselect_b32 s56, s68, s18
	s_add_i32 s21, s74, s55
	s_and_b64 s[16:17], s[16:17], exec
	s_cselect_b32 s54, s69, s21
	s_cselect_b32 s17, s51, s77
	s_cselect_b32 s16, s50, s76
	s_cselect_b32 s19, s53, s7
	s_cselect_b32 s18, s52, s6
	s_or_b32 s21, s56, 0x80
	s_or_b32 s57, s54, 0x80
	s_add_i32 s55, s55, s75
	s_add_i32 s100, s55, 0xfffe0000
	s_mov_b32 m0, s41
	s_nop 0
	buffer_load_dwordx4 v199, s[8:11], s100 offen lds
	s_mov_b32 m0, s33
	s_nop 0
	buffer_load_dwordx4 v228, s[8:11], s100 offen lds
	s_mov_b32 m0, s45
	ds_read_b128 v[162:165], v231
	ds_read_b128 v[166:169], v231 offset:1024
	ds_read_b128 v[170:173], v231 offset:2048
	ds_read_b128 v[174:177], v231 offset:3072
	ds_read_b128 v[178:181], v231 offset:4096
	ds_read_b128 v[182:185], v231 offset:5120
	ds_read_b128 v[186:189], v231 offset:6144
	ds_read_b128 v[190:193], v231 offset:7168
	buffer_load_dwordx4 v199, s[8:11], s55 offen lds
	s_mov_b32 m0, s46
	s_nop 0
	buffer_load_dwordx4 v228, s[8:11], s55 offen lds
	s_waitcnt vmcnt(8)
	s_waitcnt lgkmcnt(0)
	s_setprio 1
	s_barrier
	v_mfma_f32_16x16x32_bf16 v[126:129], v[130:133], v[162:165], v[126:129]
	v_mfma_f32_16x16x32_bf16 v[122:125], v[138:141], v[162:165], v[122:125]
	v_mfma_f32_16x16x32_bf16 v[118:121], v[130:133], v[170:173], v[118:121]
	v_mfma_f32_16x16x32_bf16 v[114:117], v[138:141], v[170:173], v[114:117]
	v_mfma_f32_16x16x32_bf16 v[110:113], v[130:133], v[178:181], v[110:113]
	v_mfma_f32_16x16x32_bf16 v[106:109], v[138:141], v[178:181], v[106:109]
	v_mfma_f32_16x16x32_bf16 v[102:105], v[130:133], v[186:189], v[102:105]
	v_mfma_f32_16x16x32_bf16 v[98:101], v[138:141], v[186:189], v[98:101]
	v_mfma_f32_16x16x32_bf16 v[126:129], v[134:137], v[166:169], v[126:129]
	v_mfma_f32_16x16x32_bf16 v[122:125], v[142:145], v[166:169], v[122:125]
	v_mfma_f32_16x16x32_bf16 v[118:121], v[134:137], v[174:177], v[118:121]
	v_mfma_f32_16x16x32_bf16 v[114:117], v[142:145], v[174:177], v[114:117]
	v_mfma_f32_16x16x32_bf16 v[110:113], v[134:137], v[182:185], v[110:113]
	v_mfma_f32_16x16x32_bf16 v[106:109], v[142:145], v[182:185], v[106:109]
	v_mfma_f32_16x16x32_bf16 v[102:105], v[134:137], v[190:193], v[102:105]
	v_mfma_f32_16x16x32_bf16 v[98:101], v[142:145], v[190:193], v[98:101]
	v_mfma_f32_16x16x32_bf16 v[94:97], v[146:149], v[162:165], v[94:97]
	v_mfma_f32_16x16x32_bf16 v[90:93], v[154:157], v[162:165], v[90:93]
	v_mfma_f32_16x16x32_bf16 v[86:89], v[146:149], v[170:173], v[86:89]
	v_mfma_f32_16x16x32_bf16 v[82:85], v[154:157], v[170:173], v[82:85]
	v_mfma_f32_16x16x32_bf16 v[78:81], v[146:149], v[178:181], v[78:81]
	v_mfma_f32_16x16x32_bf16 v[74:77], v[154:157], v[178:181], v[74:77]
	v_mfma_f32_16x16x32_bf16 v[70:73], v[146:149], v[186:189], v[70:73]
	v_mfma_f32_16x16x32_bf16 v[66:69], v[154:157], v[186:189], v[66:69]
	v_mfma_f32_16x16x32_bf16 v[94:97], v[150:153], v[166:169], v[94:97]
	v_mfma_f32_16x16x32_bf16 v[90:93], v[158:161], v[166:169], v[90:93]
	v_mfma_f32_16x16x32_bf16 v[86:89], v[150:153], v[174:177], v[86:89]
	v_mfma_f32_16x16x32_bf16 v[82:85], v[158:161], v[174:177], v[82:85]
	v_mfma_f32_16x16x32_bf16 v[78:81], v[150:153], v[182:185], v[78:81]
	v_mfma_f32_16x16x32_bf16 v[74:77], v[158:161], v[182:185], v[74:77]
	v_mfma_f32_16x16x32_bf16 v[70:73], v[150:153], v[190:193], v[70:73]
	v_mfma_f32_16x16x32_bf16 v[66:69], v[158:161], v[190:193], v[66:69]
	s_barrier
	s_setprio 0
	s_mov_b32 m0, s92
	ds_read_b128 v[162:165], v231 offset:16384
	ds_read_b128 v[166:169], v231 offset:17408
	ds_read_b128 v[170:173], v231 offset:18432
	ds_read_b128 v[174:177], v231 offset:19456
	ds_read_b128 v[178:181], v231 offset:20480
	ds_read_b128 v[182:185], v231 offset:21504
	ds_read_b128 v[186:189], v231 offset:22528
	ds_read_b128 v[190:193], v231 offset:23552
	buffer_load_dwordx4 v227, s[16:19], s54 offen lds
	s_mov_b32 m0, s93
	s_add_i32 s55, s54, 0x20000
	buffer_load_dwordx4 v229, s[16:19], s54 offen lds
	s_mov_b32 m0, s94
	s_nop 0
	buffer_load_dwordx4 v227, s[16:19], s55 offen lds
	s_mov_b32 m0, s95
	s_nop 0
	buffer_load_dwordx4 v229, s[16:19], s55 offen lds
	s_waitcnt vmcnt(6)
	s_waitcnt lgkmcnt(0)
	s_setprio 1
	s_barrier
	v_mfma_f32_16x16x32_bf16 v[62:65], v[130:133], v[162:165], v[62:65]
	v_mfma_f32_16x16x32_bf16 v[58:61], v[138:141], v[162:165], v[58:61]
	v_mfma_f32_16x16x32_bf16 v[54:57], v[130:133], v[170:173], v[54:57]
	v_mfma_f32_16x16x32_bf16 v[50:53], v[138:141], v[170:173], v[50:53]
	v_mfma_f32_16x16x32_bf16 v[46:49], v[130:133], v[178:181], v[46:49]
	v_mfma_f32_16x16x32_bf16 v[42:45], v[138:141], v[178:181], v[42:45]
	v_mfma_f32_16x16x32_bf16 v[38:41], v[130:133], v[186:189], v[38:41]
	v_mfma_f32_16x16x32_bf16 v[34:37], v[138:141], v[186:189], v[34:37]
	v_mfma_f32_16x16x32_bf16 v[62:65], v[134:137], v[166:169], v[62:65]
	v_mfma_f32_16x16x32_bf16 v[58:61], v[142:145], v[166:169], v[58:61]
	v_mfma_f32_16x16x32_bf16 v[54:57], v[134:137], v[174:177], v[54:57]
	v_mfma_f32_16x16x32_bf16 v[50:53], v[142:145], v[174:177], v[50:53]
	v_mfma_f32_16x16x32_bf16 v[46:49], v[134:137], v[182:185], v[46:49]
	v_mfma_f32_16x16x32_bf16 v[42:45], v[142:145], v[182:185], v[42:45]
	v_mfma_f32_16x16x32_bf16 v[38:41], v[134:137], v[190:193], v[38:41]
	v_mfma_f32_16x16x32_bf16 v[34:37], v[142:145], v[190:193], v[34:37]
	v_mfma_f32_16x16x32_bf16 v[30:33], v[146:149], v[162:165], v[30:33]
	v_mfma_f32_16x16x32_bf16 v[26:29], v[154:157], v[162:165], v[26:29]
	v_mfma_f32_16x16x32_bf16 v[22:25], v[146:149], v[170:173], v[22:25]
	v_mfma_f32_16x16x32_bf16 v[18:21], v[154:157], v[170:173], v[18:21]
	v_mfma_f32_16x16x32_bf16 v[14:17], v[146:149], v[178:181], v[14:17]
	v_mfma_f32_16x16x32_bf16 v[10:13], v[154:157], v[178:181], v[10:13]
	v_mfma_f32_16x16x32_bf16 v[6:9], v[146:149], v[186:189], v[6:9]
	v_mfma_f32_16x16x32_bf16 v[2:5], v[154:157], v[186:189], v[2:5]
	v_mfma_f32_16x16x32_bf16 v[30:33], v[150:153], v[166:169], v[30:33]
	v_mfma_f32_16x16x32_bf16 v[26:29], v[158:161], v[166:169], v[26:29]
	v_mfma_f32_16x16x32_bf16 v[22:25], v[150:153], v[174:177], v[22:25]
	v_mfma_f32_16x16x32_bf16 v[18:21], v[158:161], v[174:177], v[18:21]
	v_mfma_f32_16x16x32_bf16 v[14:17], v[150:153], v[182:185], v[14:17]
	v_mfma_f32_16x16x32_bf16 v[10:13], v[158:161], v[182:185], v[10:13]
	v_mfma_f32_16x16x32_bf16 v[6:9], v[150:153], v[190:193], v[6:9]
	v_mfma_f32_16x16x32_bf16 v[2:5], v[158:161], v[190:193], v[2:5]
	s_barrier
	s_setprio 0
	s_mov_b32 m0, s44
	s_nop 0
	buffer_load_dwordx4 v199, s[12:15], s56 offen lds
	s_mov_b32 m0, s36
	s_nop 0
	buffer_load_dwordx4 v228, s[12:15], s56 offen lds
	v_add_u32_e32 v0, 0x18000, v230
	ds_read_b128 v[130:133], v0
	ds_read_b128 v[134:137], v0 offset:1024
	ds_read_b128 v[138:141], v0 offset:2048
	ds_read_b128 v[142:145], v0 offset:3072
	v_add_u32_e32 v0, 0x1c000, v230
	ds_read_b128 v[146:149], v0
	ds_read_b128 v[150:153], v0 offset:1024
	ds_read_b128 v[154:157], v0 offset:2048
	ds_read_b128 v[158:161], v0 offset:3072
	s_add_i32 s56, s56, 0x20000
	s_mov_b32 m0, s37
	ds_read_b128 v[162:165], v231 offset:32768
	ds_read_b128 v[166:169], v231 offset:33792
	ds_read_b128 v[170:173], v231 offset:34816
	ds_read_b128 v[174:177], v231 offset:35840
	ds_read_b128 v[178:181], v231 offset:36864
	ds_read_b128 v[182:185], v231 offset:37888
	ds_read_b128 v[186:189], v231 offset:38912
	ds_read_b128 v[190:193], v231 offset:39936
	buffer_load_dwordx4 v199, s[12:15], s56 offen lds
	s_mov_b32 m0, s38
	s_nop 0
	buffer_load_dwordx4 v228, s[12:15], s56 offen lds
	s_waitcnt vmcnt(8)
	s_waitcnt lgkmcnt(0)
	s_setprio 1
	s_barrier
	v_mfma_f32_16x16x32_bf16 v[126:129], v[130:133], v[162:165], v[126:129]
	v_mfma_f32_16x16x32_bf16 v[122:125], v[138:141], v[162:165], v[122:125]
	v_mfma_f32_16x16x32_bf16 v[118:121], v[130:133], v[170:173], v[118:121]
	v_mfma_f32_16x16x32_bf16 v[114:117], v[138:141], v[170:173], v[114:117]
	v_mfma_f32_16x16x32_bf16 v[110:113], v[130:133], v[178:181], v[110:113]
	v_mfma_f32_16x16x32_bf16 v[106:109], v[138:141], v[178:181], v[106:109]
	v_mfma_f32_16x16x32_bf16 v[102:105], v[130:133], v[186:189], v[102:105]
	v_mfma_f32_16x16x32_bf16 v[98:101], v[138:141], v[186:189], v[98:101]
	v_mfma_f32_16x16x32_bf16 v[126:129], v[134:137], v[166:169], v[126:129]
	v_mfma_f32_16x16x32_bf16 v[122:125], v[142:145], v[166:169], v[122:125]
	v_mfma_f32_16x16x32_bf16 v[118:121], v[134:137], v[174:177], v[118:121]
	v_mfma_f32_16x16x32_bf16 v[114:117], v[142:145], v[174:177], v[114:117]
	v_mfma_f32_16x16x32_bf16 v[110:113], v[134:137], v[182:185], v[110:113]
	v_mfma_f32_16x16x32_bf16 v[106:109], v[142:145], v[182:185], v[106:109]
	v_mfma_f32_16x16x32_bf16 v[102:105], v[134:137], v[190:193], v[102:105]
	v_mfma_f32_16x16x32_bf16 v[98:101], v[142:145], v[190:193], v[98:101]
	v_mfma_f32_16x16x32_bf16 v[94:97], v[146:149], v[162:165], v[94:97]
	v_mfma_f32_16x16x32_bf16 v[90:93], v[154:157], v[162:165], v[90:93]
	v_mfma_f32_16x16x32_bf16 v[86:89], v[146:149], v[170:173], v[86:89]
	v_mfma_f32_16x16x32_bf16 v[82:85], v[154:157], v[170:173], v[82:85]
	v_mfma_f32_16x16x32_bf16 v[78:81], v[146:149], v[178:181], v[78:81]
	v_mfma_f32_16x16x32_bf16 v[74:77], v[154:157], v[178:181], v[74:77]
	v_mfma_f32_16x16x32_bf16 v[70:73], v[146:149], v[186:189], v[70:73]
	v_mfma_f32_16x16x32_bf16 v[66:69], v[154:157], v[186:189], v[66:69]
	v_mfma_f32_16x16x32_bf16 v[94:97], v[150:153], v[166:169], v[94:97]
	v_mfma_f32_16x16x32_bf16 v[90:93], v[158:161], v[166:169], v[90:93]
	v_mfma_f32_16x16x32_bf16 v[86:89], v[150:153], v[174:177], v[86:89]
	v_mfma_f32_16x16x32_bf16 v[82:85], v[158:161], v[174:177], v[82:85]
	v_mfma_f32_16x16x32_bf16 v[78:81], v[150:153], v[182:185], v[78:81]
	v_mfma_f32_16x16x32_bf16 v[74:77], v[158:161], v[182:185], v[74:77]
	v_mfma_f32_16x16x32_bf16 v[70:73], v[150:153], v[190:193], v[70:73]
	v_mfma_f32_16x16x32_bf16 v[66:69], v[158:161], v[190:193], v[66:69]
	s_barrier
; #define PG8_STAGE(bufoff, gbase, voff) do { const Src _g = (gbase); _Pragma("unroll") for (int _i = 0; _i < 2; ++_i) \
;         __builtin_amdgcn_raw_ptr_buffer_load_lds(_g.r, (LAS unsigned*)(lds + (bufoff) + ldsw + _i * 8192), 16, (voff)[_i], _g.o, 0, 0); } while (0)
; #define PG8_WAIT_V(n) asm volatile("s_waitcnt vmcnt(" #n ")" ::: "memory")
; template <class Epi, bool ALIGN_EPI, bool SP2, class Hook>
; __device__ __forceinline__ void gemm_phase(LAS unsigned char* lds, const Gemm g, const StaticOrder& S, const Epi& E, Acc& acc, const bool fresh, const Hook& H, const int wave_id) {
;     ...
;         for (int t = t0; t < nt; t += 2) {
;             const bool last = (t == nt - 2);
;             const Src a1 = cA + (size_t)(t + 1) * kstep;
;             const Src a2 = last ? nA : cA + (size_t)(t + 2) * kstep, b2 = last ? nB : cB + (size_t)(t + 2) * kstep;
;             const Src a3 = a2 + kstep, b3 = b2 + kstep;
;             if (last && has_next) H(nxt);
;             if constexpr (SP2) {
;             PG8_TRIP_SP2(PG8_WAIT_V(8));
;             } else {
;             PG8_LDB(B0, 0, 0); PG8_SCHED; PG8_LDA(At, 0, 0); PG8_STAGE(PG8_SA(1, 1), a1 + hstepA, voffA);
;             PG8_WAIT_L(8); PG8_BAR; PG8_WAIT_L(0); PG8_MMA(0, 0, At, B0); PG8_BAR; PG8_SCHED;
;             PG8_LDB(B1, 0, 1); PG8_STAGE(PG8_SB(0, 0), b2, voffB);
;             PG8_BAR; PG8_WAIT_L(0); PG8_MMA(0, 1, At, B1); PG8_BAR;
;             PG8_LDA(At, 0, 1); PG8_STAGE(PG8_SA(0, 0), a2, voffA);
;             PG8_BAR; PG8_WAIT_L(0); PG8_MMA(1, 0, At, B0); PG8_BAR; PG8_SCHED;
;             PG8_STAGE(PG8_SB(0, 1), b2 + hstep, voffB);
;             PG8_WAIT_V(6); PG8_BAR; PG8_MMA(1, 1, At, B1); PG8_BAR;
;             PG8_LDB(B0, 1, 0); PG8_SCHED; PG8_LDA(At, 1, 0); PG8_STAGE(PG8_SA(0, 1), a2 + hstepA, voffA);
;             PG8_WAIT_L(8); PG8_BAR; PG8_WAIT_L(0); PG8_MMA(0, 0, At, B0); PG8_BAR; PG8_SCHED;
;             PG8_LDB(B1, 1, 1); PG8_STAGE(PG8_SB(1, 0), b3, voffB);
;             PG8_BAR; PG8_WAIT_L(0); PG8_MMA(0, 1, At, B1); PG8_BAR;
;             PG8_LDA(At, 1, 1); PG8_STAGE(PG8_SA(1, 0), a3, voffA);
;             PG8_BAR; PG8_WAIT_L(0); PG8_MMA(1, 0, At, B0); PG8_BAR; PG8_SCHED;
;             PG8_STAGE(PG8_SB(1, 1), b3 + hstep, voffB);
;             PG8_WAIT_V(6); PG8_BAR; PG8_MMA(1, 1, At, B1); PG8_BAR;
;             }
;         }
;         if constexpr (ALIGN_EPI) { if (wr == 0) PG8_BAR; }
	s_setprio 0
	s_mov_b32 m0, s39
	ds_read_b128 v[162:165], v231 offset:49152
	ds_read_b128 v[166:169], v231 offset:50176
	ds_read_b128 v[170:173], v231 offset:51200
	ds_read_b128 v[174:177], v231 offset:52224
	ds_read_b128 v[178:181], v231 offset:53248
	ds_read_b128 v[182:185], v231 offset:54272
	ds_read_b128 v[186:189], v231 offset:55296
	ds_read_b128 v[190:193], v231 offset:56320
	buffer_load_dwordx4 v227, s[16:19], s57 offen lds
	s_mov_b32 m0, s40
	s_add_i32 s54, s54, 0x20080
	buffer_load_dwordx4 v229, s[16:19], s57 offen lds
	s_mov_b32 m0, s43
	s_nop 0
	buffer_load_dwordx4 v227, s[16:19], s54 offen lds
	s_mov_b32 m0, s42
	s_nop 0
	buffer_load_dwordx4 v229, s[16:19], s54 offen lds
	s_waitcnt vmcnt(6)
	s_waitcnt lgkmcnt(0)
	s_setprio 1
	s_barrier
	v_mfma_f32_16x16x32_bf16 v[62:65], v[130:133], v[162:165], v[62:65]
	v_mfma_f32_16x16x32_bf16 v[58:61], v[138:141], v[162:165], v[58:61]
	v_mfma_f32_16x16x32_bf16 v[54:57], v[130:133], v[170:173], v[54:57]
	v_mfma_f32_16x16x32_bf16 v[50:53], v[138:141], v[170:173], v[50:53]
	v_mfma_f32_16x16x32_bf16 v[46:49], v[130:133], v[178:181], v[46:49]
	v_mfma_f32_16x16x32_bf16 v[42:45], v[138:141], v[178:181], v[42:45]
	v_mfma_f32_16x16x32_bf16 v[38:41], v[130:133], v[186:189], v[38:41]
	v_mfma_f32_16x16x32_bf16 v[34:37], v[138:141], v[186:189], v[34:37]
	v_mfma_f32_16x16x32_bf16 v[62:65], v[134:137], v[166:169], v[62:65]
	v_mfma_f32_16x16x32_bf16 v[58:61], v[142:145], v[166:169], v[58:61]
	v_mfma_f32_16x16x32_bf16 v[54:57], v[134:137], v[174:177], v[54:57]
	v_mfma_f32_16x16x32_bf16 v[50:53], v[142:145], v[174:177], v[50:53]
	v_mfma_f32_16x16x32_bf16 v[46:49], v[134:137], v[182:185], v[46:49]
	v_mfma_f32_16x16x32_bf16 v[42:45], v[142:145], v[182:185], v[42:45]
	v_mfma_f32_16x16x32_bf16 v[38:41], v[134:137], v[190:193], v[38:41]
	v_mfma_f32_16x16x32_bf16 v[34:37], v[142:145], v[190:193], v[34:37]
	v_mfma_f32_16x16x32_bf16 v[30:33], v[146:149], v[162:165], v[30:33]
	v_mfma_f32_16x16x32_bf16 v[26:29], v[154:157], v[162:165], v[26:29]
	v_mfma_f32_16x16x32_bf16 v[22:25], v[146:149], v[170:173], v[22:25]
	v_mfma_f32_16x16x32_bf16 v[18:21], v[154:157], v[170:173], v[18:21]
	v_mfma_f32_16x16x32_bf16 v[14:17], v[146:149], v[178:181], v[14:17]
	v_mfma_f32_16x16x32_bf16 v[10:13], v[154:157], v[178:181], v[10:13]
	v_mfma_f32_16x16x32_bf16 v[6:9], v[146:149], v[186:189], v[6:9]
	v_mfma_f32_16x16x32_bf16 v[2:5], v[154:157], v[186:189], v[2:5]
	v_mfma_f32_16x16x32_bf16 v[30:33], v[150:153], v[166:169], v[30:33]
	v_mfma_f32_16x16x32_bf16 v[26:29], v[158:161], v[166:169], v[26:29]
	v_mfma_f32_16x16x32_bf16 v[22:25], v[150:153], v[174:177], v[22:25]
	v_mfma_f32_16x16x32_bf16 v[18:21], v[158:161], v[174:177], v[18:21]
	v_mfma_f32_16x16x32_bf16 v[14:17], v[150:153], v[182:185], v[14:17]
	v_mfma_f32_16x16x32_bf16 v[10:13], v[158:161], v[182:185], v[10:13]
	v_mfma_f32_16x16x32_bf16 v[6:9], v[150:153], v[190:193], v[6:9]
	v_mfma_f32_16x16x32_bf16 v[2:5], v[158:161], v[190:193], v[2:5]
	s_barrier
	s_setprio 0
	s_add_i32 s101, s20, 2
	s_cmp_gt_u32 s20, 5
	s_cbranch_scc1 .LBB0_1032
	s_mov_b32 s20, s101
	s_branch .LBB0_951
.LBB0_1032:
	s_mov_b32 m0, s41
	s_nop 0
	buffer_load_dwordx4 v199, s[12:15], s21 offen lds
	s_mov_b32 m0, s33
	s_nop 0
	buffer_load_dwordx4 v228, s[12:15], s21 offen lds
	v_readlane_b32 s2, v251, 45
	v_readlane_b32 s3, v251, 46
	s_and_b64 vcc, exec, s[2:3]
	s_cbranch_vccz .LBB0_1034
	s_barrier
